# strategy 7: 116 redundant canonicalising v_max dropped from the VALU-bound up-projection epilogue; EpiVB sum-of-squares loads hoisted with counted waits
# speedup vs baseline: 1.0016x; 1.0016x over previous
; __device__ __forceinline__ u32x4 pack8(f32x4 a, f32x4 b) { u32x4 w; w.x = cvt_pk_bf16(a[0], a[1]); w.y = cvt_pk_bf16(a[2], a[3]); w.z = cvt_pk_bf16(b[0], b[1]); w.w = cvt_pk_bf16(b[2], b[3]); return w; }
; __device__ __forceinline__ float rs_of(const float* ss, int row) { return 1.0f / sqrtf(ss[row] * (1.0f / 2048.0f) + 1e-5f); }
;     __device__ __forceinline__ void operator()(const f32x4 (&acc)[2][2][4][2], const Unit& u, int wr, int wc, int fr, int fq) const {
;         const int row0 = u.pm * BM + wr * 64 + fr;
;         if (u.pn < 16) {
;             const int col = u.pn * 128 + wc * 32 + 8 * fq;
; #pragma unroll
;             for (int ai = 0; ai < 2; ++ai)
; #pragma unroll
;                 for (int m = 0; m < 4; ++m) {
;                     const int row = row0 + ai * HALF + m * 16; const float rr = rs_of(ss, row), r2 = rr * rr;
;                     bf16_t* p = V + (size_t)row * 2048 + col;
;                     *(u32x4*)p = pack8(acc[ai][0][m][0] * acc[ai][1][m][0] * r2, acc[ai][0][m][1] * acc[ai][1][m][1] * r2);
;                 }
.LBB0_425:
	global_load_dword v182, v[136:137], off offset:64
	global_load_dword v183, v[136:137], off offset:128
	global_load_dword v184, v[136:137], off offset:192
	global_load_dword v185, v[136:137], off offset:512
	global_load_dword v186, v[136:137], off offset:576
	global_load_dword v187, v[136:137], off offset:640
	global_load_dword v188, v[136:137], off offset:704
	v_lshl_or_b32 v148, s63, 7, v157
	v_ashrrev_i32_e32 v149, 31, v148
	v_mul_f32_e32 v150, v144, v144
	v_lshl_add_u64 v[144:145], s[12:13], 0, v[146:147]
	v_lshlrev_b64 v[146:147], 1, v[148:149]
	v_pk_mul_f32 v[118:119], v[126:127], v[118:119]
	v_pk_mul_f32 v[116:117], v[124:125], v[116:117]
	v_pk_mul_f32 v[114:115], v[122:123], v[114:115]
	v_pk_mul_f32 v[112:113], v[120:121], v[112:113]
	v_lshl_add_u64 v[144:145], v[144:145], 0, v[146:147]
	v_pk_mul_f32 v[118:119], v[118:119], v[150:151] op_sel_hi:[1,0]
	v_pk_mul_f32 v[116:117], v[116:117], v[150:151] op_sel_hi:[1,0]
	v_pk_mul_f32 v[120:121], v[114:115], v[150:151] op_sel_hi:[1,0]
	v_pk_mul_f32 v[114:115], v[112:113], v[150:151] op_sel_hi:[1,0]
	v_cvt_pk_bf16_f32 v112, v116, v117
	v_cvt_pk_bf16_f32 v113, v118, v119
	v_ashrrev_i32_e32 v143, 31, v142
	v_cvt_pk_bf16_f32 v114, v114, v115
	v_cvt_pk_bf16_f32 v115, v120, v121
	global_store_dwordx4 v[144:145], v[112:115], off
	v_pk_mul_f32 v[96:97], v[104:105], v[96:97]
	v_pk_mul_f32 v[100:101], v[108:109], v[100:101]
	v_lshl_add_u64 v[112:113], v[142:143], 2, s[14:15]
	v_pk_mul_f32 v[102:103], v[110:111], v[102:103]
	v_pk_mul_f32 v[98:99], v[106:107], v[98:99]
	v_ashrrev_i32_e32 v141, 31, v140
	v_lshl_add_u64 v[106:107], v[140:141], 2, s[14:15]
	v_pk_mul_f32 v[80:81], v[88:89], v[80:81]
	v_pk_mul_f32 v[84:85], v[92:93], v[84:85]
	v_pk_mul_f32 v[86:87], v[94:95], v[86:87]
	v_pk_mul_f32 v[82:83], v[90:91], v[82:83]
	v_ashrrev_i32_e32 v139, 31, v138
	v_lshl_add_u64 v[90:91], v[138:139], 2, s[14:15]
	v_pk_mul_f32 v[66:67], v[74:75], v[66:67]
	v_pk_mul_f32 v[68:69], v[76:77], v[68:69]
	v_pk_mul_f32 v[70:71], v[78:79], v[70:71]
	v_pk_mul_f32 v[64:65], v[72:73], v[64:65]
	v_lshlrev_b64 v[72:73], 12, v[138:139]
	v_lshl_add_u64 v[72:73], s[12:13], 0, v[72:73]
	v_lshl_add_u64 v[72:73], v[72:73], 0, v[146:147]
	v_pk_mul_f32 v[54:55], v[62:63], v[54:55]
	v_pk_mul_f32 v[48:49], v[56:57], v[48:49]
	v_pk_mul_f32 v[50:51], v[58:59], v[50:51]
	v_pk_mul_f32 v[52:53], v[60:61], v[52:53]
	v_pk_mul_f32 v[38:39], v[46:47], v[38:39]
	v_pk_mul_f32 v[32:33], v[40:41], v[32:33]
	v_pk_mul_f32 v[34:35], v[42:43], v[34:35]
	v_pk_mul_f32 v[36:37], v[44:45], v[36:37]
	v_pk_mul_f32 v[22:23], v[30:31], v[22:23]
	v_pk_mul_f32 v[16:17], v[24:25], v[16:17]
	v_pk_mul_f32 v[18:19], v[26:27], v[18:19]
	v_pk_mul_f32 v[20:21], v[28:29], v[20:21]
	v_pk_mul_f32 v[2:3], v[6:7], v[2:3]
	v_pk_mul_f32 v[8:9], v[12:13], v[8:9]
	v_pk_mul_f32 v[0:1], v[4:5], v[0:1]
	v_pk_mul_f32 v[10:11], v[14:15], v[10:11]
	s_waitcnt vmcnt(7)
	v_fmamk_f32 v104, v182, 0x3a000000, v205
	v_mul_f32_e32 v105, 0x4f800000, v104
	v_cmp_gt_f32_e32 vcc, s83, v104
	s_nop 1
	v_cndmask_b32_e32 v108, v104, v105, vcc
	v_sqrt_f32_e32 v109, v108
	v_lshlrev_b64 v[104:105], 12, v[142:143]
	v_lshl_add_u64 v[104:105], s[12:13], 0, v[104:105]
	v_lshl_add_u64 v[104:105], v[104:105], 0, v[146:147]
	v_add_u32_e32 v110, -1, v109
	v_add_u32_e32 v111, 1, v109
	v_fma_f32 v112, -v110, v109, v108
	v_fma_f32 v113, -v111, v109, v108
	v_cmp_ge_f32_e64 s[0:1], 0, v112
	s_nop 1
	v_cndmask_b32_e64 v109, v109, v110, s[0:1]
	v_cmp_lt_f32_e64 s[0:1], 0, v113
	s_nop 1
	v_cndmask_b32_e64 v109, v109, v111, s[0:1]
	v_mul_f32_e32 v110, 0x37800000, v109
	v_cndmask_b32_e32 v109, v109, v110, vcc
	v_cmp_class_f32_e32 vcc, v108, v206
	s_nop 1
	v_cndmask_b32_e32 v108, v109, v108, vcc
	v_div_scale_f32 v109, s[0:1], v108, v108, 1.0
	v_rcp_f32_e32 v110, v109
	v_div_scale_f32 v111, vcc, 1.0, v108, 1.0
	v_fma_f32 v112, -v109, v110, 1.0
	v_fmac_f32_e32 v110, v112, v110
	v_mul_f32_e32 v112, v111, v110
	v_fma_f32 v113, -v109, v112, v111
	v_fmac_f32_e32 v112, v113, v110
	v_fma_f32 v109, -v109, v112, v111
	v_div_fmas_f32 v109, v109, v110, v112
	v_div_fixup_f32 v108, v109, v108, 1.0
	v_mul_f32_e32 v108, v108, v108
	v_pk_mul_f32 v[110:111], v[98:99], v[108:109] op_sel_hi:[1,0]
	v_pk_mul_f32 v[98:99], v[96:97], v[108:109] op_sel_hi:[1,0]
	v_pk_mul_f32 v[102:103], v[102:103], v[108:109] op_sel_hi:[1,0]
	v_pk_mul_f32 v[100:101], v[100:101], v[108:109] op_sel_hi:[1,0]
	s_nop 0
	v_cvt_pk_bf16_f32 v96, v100, v101
	v_cvt_pk_bf16_f32 v97, v102, v103
	v_cvt_pk_bf16_f32 v98, v98, v99
	v_cvt_pk_bf16_f32 v99, v110, v111
	global_store_dwordx4 v[104:105], v[96:99], off
	s_nop 1
	s_waitcnt vmcnt(7)
	v_fmamk_f32 v88, v183, 0x3a000000, v205
	v_mul_f32_e32 v89, 0x4f800000, v88
	v_cmp_gt_f32_e32 vcc, s83, v88
	s_nop 1
	v_cndmask_b32_e32 v92, v88, v89, vcc
	v_sqrt_f32_e32 v93, v92
	v_lshlrev_b64 v[88:89], 12, v[140:141]
	v_lshl_add_u64 v[88:89], s[12:13], 0, v[88:89]
	v_lshl_add_u64 v[88:89], v[88:89], 0, v[146:147]
	v_add_u32_e32 v94, -1, v93
	v_add_u32_e32 v95, 1, v93
	v_fma_f32 v96, -v94, v93, v92
	v_fma_f32 v97, -v95, v93, v92
	v_cmp_ge_f32_e64 s[0:1], 0, v96
	s_nop 1
	v_cndmask_b32_e64 v93, v93, v94, s[0:1]
	v_cmp_lt_f32_e64 s[0:1], 0, v97
	s_nop 1
	v_cndmask_b32_e64 v93, v93, v95, s[0:1]
	v_mul_f32_e32 v94, 0x37800000, v93
	v_cndmask_b32_e32 v93, v93, v94, vcc
	v_cmp_class_f32_e32 vcc, v92, v206
	s_nop 1
	v_cndmask_b32_e32 v92, v93, v92, vcc
	v_div_scale_f32 v93, s[0:1], v92, v92, 1.0
	v_rcp_f32_e32 v94, v93
	v_div_scale_f32 v95, vcc, 1.0, v92, 1.0
	v_fma_f32 v96, -v93, v94, 1.0
	v_fmac_f32_e32 v94, v96, v94
	v_mul_f32_e32 v96, v95, v94
	v_fma_f32 v97, -v93, v96, v95
	v_fmac_f32_e32 v96, v97, v94
	v_fma_f32 v93, -v93, v96, v95
	v_div_fmas_f32 v93, v93, v94, v96
	v_div_fixup_f32 v92, v93, v92, 1.0
	v_mul_f32_e32 v92, v92, v92
	v_pk_mul_f32 v[94:95], v[82:83], v[92:93] op_sel_hi:[1,0]
	v_pk_mul_f32 v[82:83], v[80:81], v[92:93] op_sel_hi:[1,0]
	v_pk_mul_f32 v[86:87], v[86:87], v[92:93] op_sel_hi:[1,0]
	v_pk_mul_f32 v[84:85], v[84:85], v[92:93] op_sel_hi:[1,0]
	s_nop 0
	v_cvt_pk_bf16_f32 v80, v84, v85
	v_cvt_pk_bf16_f32 v81, v86, v87
	v_cvt_pk_bf16_f32 v82, v82, v83
	v_cvt_pk_bf16_f32 v83, v94, v95
	global_store_dwordx4 v[88:89], v[80:83], off
	s_nop 1
	s_waitcnt vmcnt(7)
; __device__ __forceinline__ u32x4 pack8(f32x4 a, f32x4 b) { u32x4 w; w.x = cvt_pk_bf16(a[0], a[1]); w.y = cvt_pk_bf16(a[2], a[3]); w.z = cvt_pk_bf16(b[0], b[1]); w.w = cvt_pk_bf16(b[2], b[3]); return w; }
; __device__ __forceinline__ float rs_of(const float* ss, int row) { return 1.0f / sqrtf(ss[row] * (1.0f / 2048.0f) + 1e-5f); }
;     __device__ __forceinline__ void operator()(const f32x4 (&acc)[2][2][4][2], const Unit& u, int wr, int wc, int fr, int fq) const {
;         const int row0 = u.pm * BM + wr * 64 + fr;
;         if (u.pn < 16) {
;             const int col = u.pn * 128 + wc * 32 + 8 * fq;
; #pragma unroll
;             for (int ai = 0; ai < 2; ++ai)
; #pragma unroll
;                 for (int m = 0; m < 4; ++m) {
;                     const int row = row0 + ai * HALF + m * 16; const float rr = rs_of(ss, row), r2 = rr * rr;
;                     bf16_t* p = V + (size_t)row * 2048 + col;
;                     *(u32x4*)p = pack8(acc[ai][0][m][0] * acc[ai][1][m][0] * r2, acc[ai][0][m][1] * acc[ai][1][m][1] * r2);
;                 }
	v_fmamk_f32 v74, v184, 0x3a000000, v205
	v_mul_f32_e32 v75, 0x4f800000, v74
	v_cmp_gt_f32_e32 vcc, s83, v74
	s_nop 1
	v_cndmask_b32_e32 v74, v74, v75, vcc
	v_sqrt_f32_e32 v75, v74
	s_nop 0
	v_add_u32_e32 v76, -1, v75
	v_add_u32_e32 v77, 1, v75
	v_fma_f32 v78, -v76, v75, v74
	v_fma_f32 v79, -v77, v75, v74
	v_cmp_ge_f32_e64 s[0:1], 0, v78
	s_nop 1
	v_cndmask_b32_e64 v75, v75, v76, s[0:1]
	v_cmp_lt_f32_e64 s[0:1], 0, v79
	s_nop 1
	v_cndmask_b32_e64 v75, v75, v77, s[0:1]
	v_mul_f32_e32 v76, 0x37800000, v75
	v_cndmask_b32_e32 v75, v75, v76, vcc
	v_cmp_class_f32_e32 vcc, v74, v206
	s_nop 1
	v_cndmask_b32_e32 v74, v75, v74, vcc
	v_div_scale_f32 v75, s[0:1], v74, v74, 1.0
	v_rcp_f32_e32 v76, v75
	v_div_scale_f32 v77, vcc, 1.0, v74, 1.0
	v_fma_f32 v78, -v75, v76, 1.0
	v_fmac_f32_e32 v76, v78, v76
	v_mul_f32_e32 v78, v77, v76
	v_fma_f32 v79, -v75, v78, v77
	v_fmac_f32_e32 v78, v79, v76
	v_fma_f32 v75, -v75, v78, v77
	v_div_fmas_f32 v75, v75, v76, v78
	v_div_fixup_f32 v74, v75, v74, 1.0
	v_mul_f32_e32 v74, v74, v74
	v_pk_mul_f32 v[76:77], v[66:67], v[74:75] op_sel_hi:[1,0]
	v_pk_mul_f32 v[66:67], v[64:65], v[74:75] op_sel_hi:[1,0]
	v_pk_mul_f32 v[70:71], v[70:71], v[74:75] op_sel_hi:[1,0]
	v_pk_mul_f32 v[68:69], v[68:69], v[74:75] op_sel_hi:[1,0]
	s_nop 0
	v_cvt_pk_bf16_f32 v64, v68, v69
	v_cvt_pk_bf16_f32 v65, v70, v71
	v_cvt_pk_bf16_f32 v66, v66, v67
	v_cvt_pk_bf16_f32 v67, v76, v77
	global_store_dwordx4 v[72:73], v[64:67], off
	s_nop 1
	s_waitcnt vmcnt(7)
	v_fmamk_f32 v62, v185, 0x3a000000, v205
	v_mul_f32_e32 v63, 0x4f800000, v62
	v_cmp_gt_f32_e32 vcc, s83, v62
	s_nop 1
	v_cndmask_b32_e32 v62, v62, v63, vcc
	v_sqrt_f32_e32 v63, v62
	s_nop 0
	v_add_u32_e32 v56, -1, v63
	v_add_u32_e32 v57, 1, v63
	v_fma_f32 v58, -v56, v63, v62
	v_fma_f32 v59, -v57, v63, v62
	v_cmp_ge_f32_e64 s[0:1], 0, v58
	s_nop 1
	v_cndmask_b32_e64 v56, v63, v56, s[0:1]
	v_cmp_lt_f32_e64 s[0:1], 0, v59
	s_nop 1
	v_cndmask_b32_e64 v56, v56, v57, s[0:1]
	v_mul_f32_e32 v57, 0x37800000, v56
	v_cndmask_b32_e32 v56, v56, v57, vcc
	v_cmp_class_f32_e32 vcc, v62, v206
	s_nop 1
	v_cndmask_b32_e32 v58, v56, v62, vcc
	v_div_scale_f32 v59, s[0:1], v58, v58, 1.0
	v_rcp_f32_e32 v60, v59
	v_add_co_u32_e32 v56, vcc, s89, v144
	v_fma_f32 v62, -v59, v60, 1.0
	s_nop 0
	v_addc_co_u32_e32 v57, vcc, 0, v145, vcc
	v_div_scale_f32 v61, vcc, 1.0, v58, 1.0
	v_fmac_f32_e32 v60, v62, v60
	v_mul_f32_e32 v62, v61, v60
	v_fma_f32 v63, -v59, v62, v61
	v_fmac_f32_e32 v62, v63, v60
	v_fma_f32 v59, -v59, v62, v61
	v_div_fmas_f32 v59, v59, v60, v62
	v_div_fixup_f32 v58, v59, v58, 1.0
	v_mul_f32_e32 v58, v58, v58
	v_pk_mul_f32 v[60:61], v[50:51], v[58:59] op_sel_hi:[1,0]
	v_pk_mul_f32 v[50:51], v[48:49], v[58:59] op_sel_hi:[1,0]
	v_pk_mul_f32 v[54:55], v[54:55], v[58:59] op_sel_hi:[1,0]
	v_pk_mul_f32 v[52:53], v[52:53], v[58:59] op_sel_hi:[1,0]
	s_nop 0
	v_cvt_pk_bf16_f32 v48, v52, v53
	v_cvt_pk_bf16_f32 v49, v54, v55
	v_cvt_pk_bf16_f32 v50, v50, v51
	v_cvt_pk_bf16_f32 v51, v60, v61
	global_store_dwordx4 v[56:57], v[48:51], off
	s_nop 1
	s_waitcnt vmcnt(7)
	v_fmamk_f32 v46, v186, 0x3a000000, v205
	v_mul_f32_e32 v47, 0x4f800000, v46
	v_cmp_gt_f32_e32 vcc, s83, v46
	s_nop 1
	v_cndmask_b32_e32 v46, v46, v47, vcc
	v_sqrt_f32_e32 v47, v46
	s_nop 0
	v_add_u32_e32 v40, -1, v47
	v_add_u32_e32 v41, 1, v47
	v_fma_f32 v42, -v40, v47, v46
	v_fma_f32 v43, -v41, v47, v46
	v_cmp_ge_f32_e64 s[0:1], 0, v42
	s_nop 1
	v_cndmask_b32_e64 v40, v47, v40, s[0:1]
	v_cmp_lt_f32_e64 s[0:1], 0, v43
	s_nop 1
	v_cndmask_b32_e64 v40, v40, v41, s[0:1]
	v_mul_f32_e32 v41, 0x37800000, v40
	v_cndmask_b32_e32 v40, v40, v41, vcc
	v_cmp_class_f32_e32 vcc, v46, v206
	s_nop 1
	v_cndmask_b32_e32 v42, v40, v46, vcc
	v_div_scale_f32 v43, s[0:1], v42, v42, 1.0
	v_rcp_f32_e32 v44, v43
	s_mov_b32 s0, 0x90000
	v_add_co_u32_e32 v40, vcc, s0, v144
	v_fma_f32 v46, -v43, v44, 1.0
	s_nop 0
	v_addc_co_u32_e32 v41, vcc, 0, v145, vcc
	v_div_scale_f32 v45, vcc, 1.0, v42, 1.0
	v_fmac_f32_e32 v44, v46, v44
	v_mul_f32_e32 v46, v45, v44
	v_fma_f32 v47, -v43, v46, v45
	v_fmac_f32_e32 v46, v47, v44
	v_fma_f32 v43, -v43, v46, v45
	v_div_fmas_f32 v43, v43, v44, v46
	v_div_fixup_f32 v42, v43, v42, 1.0
	v_mul_f32_e32 v42, v42, v42
	v_pk_mul_f32 v[44:45], v[34:35], v[42:43] op_sel_hi:[1,0]
	v_pk_mul_f32 v[34:35], v[32:33], v[42:43] op_sel_hi:[1,0]
	v_pk_mul_f32 v[38:39], v[38:39], v[42:43] op_sel_hi:[1,0]
	v_pk_mul_f32 v[36:37], v[36:37], v[42:43] op_sel_hi:[1,0]
	s_nop 0
	v_cvt_pk_bf16_f32 v32, v36, v37
	v_cvt_pk_bf16_f32 v33, v38, v39
	v_cvt_pk_bf16_f32 v34, v34, v35
	v_cvt_pk_bf16_f32 v35, v44, v45
	global_store_dwordx4 v[40:41], v[32:35], off
	s_nop 1
	s_waitcnt vmcnt(7)
; __device__ __forceinline__ u32x4 pack8(f32x4 a, f32x4 b) { u32x4 w; w.x = cvt_pk_bf16(a[0], a[1]); w.y = cvt_pk_bf16(a[2], a[3]); w.z = cvt_pk_bf16(b[0], b[1]); w.w = cvt_pk_bf16(b[2], b[3]); return w; }
; __device__ __forceinline__ float rs_of(const float* ss, int row) { return 1.0f / sqrtf(ss[row] * (1.0f / 2048.0f) + 1e-5f); }
;     __device__ __forceinline__ void operator()(const f32x4 (&acc)[2][2][4][2], const Unit& u, int wr, int wc, int fr, int fq) const {
;         const int row0 = u.pm * BM + wr * 64 + fr;
;         if (u.pn < 16) {
;             const int col = u.pn * 128 + wc * 32 + 8 * fq;
; #pragma unroll
;             for (int ai = 0; ai < 2; ++ai)
; #pragma unroll
;                 for (int m = 0; m < 4; ++m) {
;                     const int row = row0 + ai * HALF + m * 16; const float rr = rs_of(ss, row), r2 = rr * rr;
;                     bf16_t* p = V + (size_t)row * 2048 + col;
;                     *(u32x4*)p = pack8(acc[ai][0][m][0] * acc[ai][1][m][0] * r2, acc[ai][0][m][1] * acc[ai][1][m][1] * r2);
;                 }
	v_fmamk_f32 v30, v187, 0x3a000000, v205
	v_mul_f32_e32 v31, 0x4f800000, v30
	v_cmp_gt_f32_e32 vcc, s83, v30
	s_nop 1
	v_cndmask_b32_e32 v30, v30, v31, vcc
	v_sqrt_f32_e32 v31, v30
	s_nop 0
	v_add_u32_e32 v24, -1, v31
	v_add_u32_e32 v25, 1, v31
	v_fma_f32 v26, -v24, v31, v30
	v_fma_f32 v27, -v25, v31, v30
	v_cmp_ge_f32_e64 s[0:1], 0, v26
	s_nop 1
	v_cndmask_b32_e64 v24, v31, v24, s[0:1]
	v_cmp_lt_f32_e64 s[0:1], 0, v27
	s_nop 1
	v_cndmask_b32_e64 v24, v24, v25, s[0:1]
	v_mul_f32_e32 v25, 0x37800000, v24
	v_cndmask_b32_e32 v24, v24, v25, vcc
	v_cmp_class_f32_e32 vcc, v30, v206
	s_nop 1
	v_cndmask_b32_e32 v26, v24, v30, vcc
	v_div_scale_f32 v27, s[0:1], v26, v26, 1.0
	v_rcp_f32_e32 v28, v27
	s_mov_b32 s0, 0xa0000
	v_add_co_u32_e32 v24, vcc, s0, v144
	v_fma_f32 v30, -v27, v28, 1.0
	s_nop 0
	v_addc_co_u32_e32 v25, vcc, 0, v145, vcc
	v_div_scale_f32 v29, vcc, 1.0, v26, 1.0
	v_fmac_f32_e32 v28, v30, v28
	v_mul_f32_e32 v30, v29, v28
	v_fma_f32 v31, -v27, v30, v29
	v_fmac_f32_e32 v30, v31, v28
	v_fma_f32 v27, -v27, v30, v29
	v_div_fmas_f32 v27, v27, v28, v30
	v_div_fixup_f32 v26, v27, v26, 1.0
	v_mul_f32_e32 v26, v26, v26
	v_pk_mul_f32 v[28:29], v[18:19], v[26:27] op_sel_hi:[1,0]
	v_pk_mul_f32 v[18:19], v[16:17], v[26:27] op_sel_hi:[1,0]
	v_pk_mul_f32 v[22:23], v[22:23], v[26:27] op_sel_hi:[1,0]
	v_pk_mul_f32 v[20:21], v[20:21], v[26:27] op_sel_hi:[1,0]
	s_nop 0
	v_cvt_pk_bf16_f32 v16, v20, v21
	v_cvt_pk_bf16_f32 v17, v22, v23
	v_cvt_pk_bf16_f32 v18, v18, v19
	v_cvt_pk_bf16_f32 v19, v28, v29
	global_store_dwordx4 v[24:25], v[16:19], off
	s_nop 1
	s_waitcnt vmcnt(7)
	v_fmamk_f32 v16, v188, 0x3a000000, v205
	v_mul_f32_e32 v17, 0x4f800000, v16
	v_cmp_gt_f32_e32 vcc, s83, v16
	s_nop 1
	v_cndmask_b32_e32 v16, v16, v17, vcc
	v_sqrt_f32_e32 v17, v16
	s_nop 0
	v_add_u32_e32 v6, -1, v17
	v_add_u32_e32 v7, 1, v17
	v_fma_f32 v12, -v6, v17, v16
	v_fma_f32 v13, -v7, v17, v16
	v_cmp_ge_f32_e64 s[0:1], 0, v12
	s_nop 1
	v_cndmask_b32_e64 v6, v17, v6, s[0:1]
	v_cmp_lt_f32_e64 s[0:1], 0, v13
	s_nop 1
	v_cndmask_b32_e64 v6, v6, v7, s[0:1]
	v_mul_f32_e32 v7, 0x37800000, v6
	v_cndmask_b32_e32 v6, v6, v7, vcc
	v_cmp_class_f32_e32 vcc, v16, v206
	s_nop 1
	v_cndmask_b32_e32 v6, v6, v16, vcc
	v_div_scale_f32 v7, s[0:1], v6, v6, 1.0
	v_rcp_f32_e32 v12, v7
	v_div_scale_f32 v4, vcc, 1.0, v6, 1.0
	v_fma_f32 v5, -v7, v12, 1.0
	v_fmac_f32_e32 v12, v5, v12
	v_mul_f32_e32 v5, v4, v12
	v_fma_f32 v13, -v7, v5, v4
	v_fmac_f32_e32 v5, v13, v12
	v_fma_f32 v4, -v7, v5, v4
	v_div_fmas_f32 v5, v4, v12, v5
	v_div_fixup_f32 v5, v5, v6, 1.0
	v_add_co_u32_e32 v4, vcc, 0xb0000, v144
	v_mul_f32_e32 v6, v5, v5
	v_pk_mul_f32 v[12:13], v[2:3], v[6:7] op_sel_hi:[1,0]
	v_pk_mul_f32 v[2:3], v[0:1], v[6:7] op_sel_hi:[1,0]
	v_addc_co_u32_e32 v5, vcc, 0, v145, vcc
	v_pk_mul_f32 v[10:11], v[10:11], v[6:7] op_sel_hi:[1,0]
	v_pk_mul_f32 v[8:9], v[8:9], v[6:7] op_sel_hi:[1,0]
	s_nop 0
	v_cvt_pk_bf16_f32 v0, v8, v9
	v_cvt_pk_bf16_f32 v1, v10, v11
	v_cvt_pk_bf16_f32 v2, v2, v3
	v_cvt_pk_bf16_f32 v3, v12, v13
	global_store_dwordx4 v[4:5], v[0:3], off
	s_andn2_b64 vcc, exec, s[2:3]
	s_mov_b64 s[0:1], -1
	s_cbranch_vccnz .LBB0_406

; __device__ __forceinline__ u32x4 pack8(f32x4 a, f32x4 b) { u32x4 w; w.x = cvt_pk_bf16(a[0], a[1]); w.y = cvt_pk_bf16(a[2], a[3]); w.z = cvt_pk_bf16(b[0], b[1]); w.w = cvt_pk_bf16(b[2], b[3]); return w; }
; __device__ __forceinline__ float rs_of(const float* ss, int row) { return 1.0f / sqrtf(ss[row] * (1.0f / 2048.0f) + 1e-5f); }
;     __device__ __forceinline__ void operator()(const f32x4 (&acc)[2][2][4][2], const Unit& u, int wr, int wc, int fr, int fq) const {
;         const int row0 = u.pm * BM + wr * 64 + fr;
;         const bool hb = (fr & 8) != 0;
;         const int srow0 = u.pm * BM + wr * 64 + (fr & 7), scol = u.pn * BM + wc * 64 + (hb ? 32 : 0) + 8 * fq;
;         const f32x4 z = {0.f, 0.f, 0.f, 0.f};
; #pragma unroll
;         for (int ai = 0; ai < 2; ++ai)
; #pragma unroll
;             for (int m = 0; m < 4; ++m) {
;                 const int row = row0 + ai * HALF + m * 16; const float rr = ss ? rs_of(ss, row) : 1.0f;
;                 u32x4 v[2];
; #pragma unroll
;                 for (int bj = 0; bj < 2; ++bj) {
;                     f32x4 a = __builtin_elementwise_max(acc[ai][bj][m][0], z) * rr, b = __builtin_elementwise_max(acc[ai][bj][m][1], z) * rr;
;                     v[bj] = pack8(a * a, b * b);
;                 }
;                 line_xchg(v[0], v[1], hb);
;                 bf16_t* p = O + (size_t)(srow0 + ai * HALF + m * 16) * ldc + scol;
;                 __builtin_nontemporal_store(v[0], (u32x4*)p); __builtin_nontemporal_store(v[1], (u32x4*)(p + (size_t)8 * ldc));
;             }
.LBB0_717:
	v_or_b32_e32 v136, s0, v144
	v_lshl_or_b32 v138, s1, 8, v145
	v_max_f32_e32 v127, 0, v127
	v_max_f32_e32 v126, 0, v126
	v_max_f32_e32 v125, 0, v125
	v_max_f32_e32 v124, 0, v124
	v_max_f32_e32 v123, 0, v123
	v_max_f32_e32 v122, 0, v122
	v_max_f32_e32 v121, 0, v121
	v_max_f32_e32 v120, 0, v120
	v_max_f32_e32 v115, 0, v115
	v_max_f32_e32 v114, 0, v114
	v_max_f32_e32 v113, 0, v113
	v_max_f32_e32 v112, 0, v112
	v_max_f32_e32 v119, 0, v119
	v_max_f32_e32 v118, 0, v118
	v_max_f32_e32 v117, 0, v117
	v_max_f32_e32 v116, 0, v116
	v_ashrrev_i32_e32 v139, 31, v138
	v_max_f32_e32 v111, 0, v111
	v_max_f32_e32 v110, 0, v110
	v_max_f32_e32 v109, 0, v109
	v_max_f32_e32 v108, 0, v108
	v_max_f32_e32 v107, 0, v107
	v_max_f32_e32 v106, 0, v106
	v_max_f32_e32 v105, 0, v105
	v_max_f32_e32 v104, 0, v104
	v_max_f32_e32 v97, 0, v97
	v_max_f32_e32 v96, 0, v96
	v_max_f32_e32 v103, 0, v103
	v_max_f32_e32 v102, 0, v102
	v_max_f32_e32 v101, 0, v101
	v_max_f32_e32 v100, 0, v100
	v_max_f32_e32 v99, 0, v99
	v_max_f32_e32 v98, 0, v98
	v_max_f32_e32 v95, 0, v95
	v_max_f32_e32 v94, 0, v94
	s_waitcnt vmcnt(7)
	v_fmamk_f32 v137, v160, 0x3a000000, v205
	v_cmp_gt_f32_e32 vcc, s83, v137
	v_mul_f32_e32 v140, 0x4f800000, v137
	v_max_f32_e32 v93, 0, v93
	v_cndmask_b32_e32 v137, v137, v140, vcc
	v_sqrt_f32_e32 v140, v137
	v_max_f32_e32 v92, 0, v92
	v_max_f32_e32 v91, 0, v91
	v_max_f32_e32 v90, 0, v90
	v_add_u32_e32 v147, -1, v140
	v_fma_f32 v148, -v147, v140, v137
	v_cmp_ge_f32_e64 s[0:1], 0, v148
	v_add_u32_e32 v148, 1, v140
	v_max_f32_e32 v89, 0, v89
	v_cndmask_b32_e64 v147, v140, v147, s[0:1]
	v_fma_f32 v140, -v148, v140, v137
	v_cmp_lt_f32_e64 s[0:1], 0, v140
	v_max_f32_e32 v88, 0, v88
	v_max_f32_e32 v87, v87, v87
	v_cndmask_b32_e64 v140, v147, v148, s[0:1]
	v_mul_f32_e32 v147, 0x37800000, v140
	v_cndmask_b32_e32 v140, v140, v147, vcc
	v_cmp_class_f32_e32 vcc, v137, v206
	v_max_f32_e32 v86, v86, v86
	v_max_f32_e32 v85, v85, v85
	v_cndmask_b32_e32 v137, v140, v137, vcc
	v_div_scale_f32 v140, s[0:1], v137, v137, 1.0
	v_rcp_f32_e32 v147, v140
	v_max_f32_e32 v84, v84, v84
	v_max_f32_e32 v83, v83, v83
	v_max_f32_e32 v82, v82, v82
	v_fma_f32 v148, -v140, v147, 1.0
	v_fmac_f32_e32 v147, v148, v147
	v_div_scale_f32 v148, vcc, 1.0, v137, 1.0
	v_mul_f32_e32 v149, v148, v147
	v_fma_f32 v150, -v140, v149, v148
	v_fmac_f32_e32 v149, v150, v147
	v_fma_f32 v140, -v140, v149, v148
	v_div_fmas_f32 v140, v140, v147, v149
	v_div_fixup_f32 v140, v140, v137, 1.0
	v_pk_mul_f32 v[124:125], v[124:125], v[140:141] op_sel_hi:[1,0]
	v_pk_mul_f32 v[126:127], v[126:127], v[140:141] op_sel_hi:[1,0]
	v_pk_mul_f32 v[120:121], v[120:121], v[140:141] op_sel_hi:[1,0]
	v_pk_mul_f32 v[122:123], v[122:123], v[140:141] op_sel_hi:[1,0]
	v_pk_mul_f32 v[112:113], v[112:113], v[140:141] op_sel_hi:[1,0]
	v_pk_mul_f32 v[114:115], v[114:115], v[140:141] op_sel_hi:[1,0]
	v_pk_mul_f32 v[126:127], v[126:127], v[126:127]
	v_pk_mul_f32 v[124:125], v[124:125], v[124:125]
	v_pk_mul_f32 v[122:123], v[122:123], v[122:123]
	v_pk_mul_f32 v[120:121], v[120:121], v[120:121]
	v_pk_mul_f32 v[116:117], v[116:117], v[140:141] op_sel_hi:[1,0]
	v_pk_mul_f32 v[118:119], v[118:119], v[140:141] op_sel_hi:[1,0]
	v_pk_mul_f32 v[114:115], v[114:115], v[114:115]
	v_pk_mul_f32 v[112:113], v[112:113], v[112:113]
	v_cvt_pk_bf16_f32 v124, v124, v125
	v_cvt_pk_bf16_f32 v125, v126, v127
	v_cvt_pk_bf16_f32 v120, v120, v121
	v_cvt_pk_bf16_f32 v121, v122, v123
	v_pk_mul_f32 v[118:119], v[118:119], v[118:119]
	v_pk_mul_f32 v[116:117], v[116:117], v[116:117]
	v_max_f32_e32 v81, 0, v81
	v_cvt_pk_bf16_f32 v122, v116, v117
	v_cvt_pk_bf16_f32 v123, v118, v119
	v_cvt_pk_bf16_f32 v126, v112, v113
	v_cvt_pk_bf16_f32 v115, v114, v115
	v_max_f32_e32 v80, 0, v80
	v_cndmask_b32_e64 v113, v126, v120, s[2:3]
	v_cndmask_b32_e64 v114, v123, v125, s[2:3]
	v_cndmask_b32_e64 v112, v115, v121, s[2:3]
	v_mov_b32_dpp v137, v113 row_ror:8 row_mask:0xf bank_mask:0xf
	v_mov_b32_dpp v114, v114 row_ror:8 row_mask:0xf bank_mask:0xf
	v_cndmask_b32_e64 v116, v122, v124, s[2:3]
	v_mov_b32_dpp v140, v112 row_ror:8 row_mask:0xf bank_mask:0xf
	v_cndmask_b32_e64 v117, v125, v114, s[2:3]
	v_cndmask_b32_e64 v118, v120, v137, s[2:3]
	v_cndmask_b32_e64 v113, v114, v123, s[2:3]
	v_cndmask_b32_e64 v114, v137, v126, s[2:3]
	v_ashrrev_i32_e32 v137, 31, v136
	v_mov_b32_dpp v127, v116 row_ror:8 row_mask:0xf bank_mask:0xf
	v_cndmask_b32_e64 v119, v121, v140, s[2:3]
	v_lshlrev_b64 v[120:121], 14, v[136:137]
	v_cndmask_b32_e64 v112, v127, v122, s[2:3]
	v_lshl_add_u64 v[120:121], s[10:11], 0, v[120:121]
	v_lshlrev_b64 v[122:123], 1, v[138:139]
	v_cndmask_b32_e64 v116, v124, v127, s[2:3]
	v_lshl_add_u64 v[120:121], v[120:121], 0, v[122:123]
	global_store_dwordx4 v[120:121], v[116:119], off nt
	v_cndmask_b32_e64 v115, v140, v115, s[2:3]
	v_max_f32_e32 v87, 0, v87
	v_add_co_u32_e32 v116, vcc, s79, v120
	v_max_f32_e32 v86, 0, v86
	s_nop 0
	v_addc_co_u32_e32 v117, vcc, 0, v121, vcc
	global_store_dwordx4 v[116:117], v[112:115], off nt
	v_max_f32_e32 v85, 0, v85
	v_max_f32_e32 v84, 0, v84
	v_max_f32_e32 v83, 0, v83
	v_max_f32_e32 v82, 0, v82
	v_max_f32_e32 v79, v79, v79
	v_max_f32_e32 v79, 0, v79
	v_max_f32_e32 v78, 0, v78
	v_max_f32_e32 v77, 0, v77
	v_max_f32_e32 v76, 0, v76
	v_max_f32_e32 v75, 0, v75
	v_max_f32_e32 v74, 0, v74
	v_max_f32_e32 v73, 0, v73
	v_max_f32_e32 v72, 0, v72
	v_max_f32_e32 v65, 0, v65
	v_max_f32_e32 v64, 0, v64
	v_max_f32_e32 v71, 0, v71
	v_max_f32_e32 v70, 0, v70
	v_max_f32_e32 v69, 0, v69
	v_max_f32_e32 v68, 0, v68
	v_max_f32_e32 v67, 0, v67
	v_max_f32_e32 v66, 0, v66
	v_max_f32_e32 v63, 0, v63
	v_max_f32_e32 v62, 0, v62
	v_max_f32_e32 v61, 0, v61
	v_max_f32_e32 v60, 0, v60
	v_max_f32_e32 v59, 0, v59
	v_max_f32_e32 v58, 0, v58
	v_max_f32_e32 v57, 0, v57
	v_max_f32_e32 v56, 0, v56
	v_max_f32_e32 v49, 0, v49
	v_max_f32_e32 v48, 0, v48
	v_max_f32_e32 v55, 0, v55
	v_max_f32_e32 v54, 0, v54
	v_max_f32_e32 v53, 0, v53
	v_max_f32_e32 v52, 0, v52
	v_max_f32_e32 v51, 0, v51
	v_max_f32_e32 v50, 0, v50
	s_waitcnt vmcnt(8)
; __device__ __forceinline__ u32x4 pack8(f32x4 a, f32x4 b) { u32x4 w; w.x = cvt_pk_bf16(a[0], a[1]); w.y = cvt_pk_bf16(a[2], a[3]); w.z = cvt_pk_bf16(b[0], b[1]); w.w = cvt_pk_bf16(b[2], b[3]); return w; }
; __device__ __forceinline__ float rs_of(const float* ss, int row) { return 1.0f / sqrtf(ss[row] * (1.0f / 2048.0f) + 1e-5f); }
;     __device__ __forceinline__ void operator()(const f32x4 (&acc)[2][2][4][2], const Unit& u, int wr, int wc, int fr, int fq) const {
;     ...
;             for (int m = 0; m < 4; ++m) {
;                 const int row = row0 + ai * HALF + m * 16; const float rr = ss ? rs_of(ss, row) : 1.0f;
;                 u32x4 v[2];
; #pragma unroll
;                 for (int bj = 0; bj < 2; ++bj) {
;                     f32x4 a = __builtin_elementwise_max(acc[ai][bj][m][0], z) * rr, b = __builtin_elementwise_max(acc[ai][bj][m][1], z) * rr;
;                     v[bj] = pack8(a * a, b * b);
;                 }
;                 line_xchg(v[0], v[1], hb);
;                 bf16_t* p = O + (size_t)(srow0 + ai * HALF + m * 16) * ldc + scol;
;                 __builtin_nontemporal_store(v[0], (u32x4*)p); __builtin_nontemporal_store(v[1], (u32x4*)(p + (size_t)8 * ldc));
;             }
	v_fmamk_f32 v112, v161, 0x3a000000, v205
	v_cmp_gt_f32_e32 vcc, s83, v112
	v_mul_f32_e32 v113, 0x4f800000, v112
	v_max_f32_e32 v46, v46, v46
	v_cndmask_b32_e32 v112, v112, v113, vcc
	v_sqrt_f32_e32 v113, v112
	v_max_f32_e32 v45, 0, v45
	v_max_f32_e32 v44, 0, v44
	v_max_f32_e32 v43, v43, v43
	v_add_u32_e32 v114, -1, v113
	v_fma_f32 v115, -v114, v113, v112
	v_cmp_ge_f32_e64 s[0:1], 0, v115
	v_add_u32_e32 v115, 1, v113
	v_max_f32_e32 v42, v42, v42
	v_cndmask_b32_e64 v114, v113, v114, s[0:1]
	v_fma_f32 v113, -v115, v113, v112
	v_cmp_lt_f32_e64 s[0:1], 0, v113
	v_max_f32_e32 v41, 0, v41
	v_max_f32_e32 v40, 0, v40
	v_cndmask_b32_e64 v113, v114, v115, s[0:1]
	v_mul_f32_e32 v114, 0x37800000, v113
	v_cndmask_b32_e32 v113, v113, v114, vcc
	v_cmp_class_f32_e32 vcc, v112, v206
	v_max_f32_e32 v39, 0, v39
	v_max_f32_e32 v38, 0, v38
	v_cndmask_b32_e32 v112, v113, v112, vcc
	v_div_scale_f32 v113, s[0:1], v112, v112, 1.0
	v_rcp_f32_e32 v114, v113
	v_max_f32_e32 v37, 0, v37
	v_max_f32_e32 v36, 0, v36
	v_max_f32_e32 v35, v35, v35
	v_fma_f32 v115, -v113, v114, 1.0
	v_fmac_f32_e32 v114, v115, v114
	v_div_scale_f32 v115, vcc, 1.0, v112, 1.0
	v_mul_f32_e32 v116, v115, v114
	v_fma_f32 v117, -v113, v116, v115
	v_fmac_f32_e32 v116, v117, v114
	v_fma_f32 v113, -v113, v116, v115
	v_div_fmas_f32 v113, v113, v114, v116
	v_div_fixup_f32 v112, v113, v112, 1.0
	v_pk_mul_f32 v[108:109], v[108:109], v[112:113] op_sel_hi:[1,0]
	v_pk_mul_f32 v[110:111], v[110:111], v[112:113] op_sel_hi:[1,0]
	v_pk_mul_f32 v[104:105], v[104:105], v[112:113] op_sel_hi:[1,0]
	v_pk_mul_f32 v[106:107], v[106:107], v[112:113] op_sel_hi:[1,0]
	v_pk_mul_f32 v[96:97], v[96:97], v[112:113] op_sel_hi:[1,0]
	v_pk_mul_f32 v[110:111], v[110:111], v[110:111]
	v_pk_mul_f32 v[108:109], v[108:109], v[108:109]
	v_pk_mul_f32 v[106:107], v[106:107], v[106:107]
	v_pk_mul_f32 v[104:105], v[104:105], v[104:105]
	v_pk_mul_f32 v[100:101], v[100:101], v[112:113] op_sel_hi:[1,0]
	v_pk_mul_f32 v[102:103], v[102:103], v[112:113] op_sel_hi:[1,0]
	v_pk_mul_f32 v[98:99], v[98:99], v[112:113] op_sel_hi:[1,0]
	v_pk_mul_f32 v[96:97], v[96:97], v[96:97]
	v_cvt_pk_bf16_f32 v108, v108, v109
	v_cvt_pk_bf16_f32 v109, v110, v111
	v_cvt_pk_bf16_f32 v104, v104, v105
	v_cvt_pk_bf16_f32 v105, v106, v107
	v_pk_mul_f32 v[102:103], v[102:103], v[102:103]
	v_pk_mul_f32 v[100:101], v[100:101], v[100:101]
	v_pk_mul_f32 v[98:99], v[98:99], v[98:99]
	v_cvt_pk_bf16_f32 v106, v100, v101
	v_cvt_pk_bf16_f32 v107, v102, v103
	v_cvt_pk_bf16_f32 v110, v96, v97
	v_max_f32_e32 v34, v34, v34
	v_cndmask_b32_e64 v97, v110, v104, s[2:3]
	v_cvt_pk_bf16_f32 v99, v98, v99
	v_cndmask_b32_e64 v98, v107, v109, s[2:3]
	v_cndmask_b32_e64 v96, v99, v105, s[2:3]
	v_mov_b32_dpp v112, v97 row_ror:8 row_mask:0xf bank_mask:0xf
	v_cndmask_b32_e64 v102, v104, v112, s[2:3]
	v_mov_b32_dpp v113, v96 row_ror:8 row_mask:0xf bank_mask:0xf
	v_or_b32_e32 v104, 16, v136
	v_cndmask_b32_e64 v103, v105, v113, s[2:3]
	v_ashrrev_i32_e32 v105, 31, v104
	v_cndmask_b32_e64 v100, v106, v108, s[2:3]
	v_lshlrev_b64 v[104:105], 14, v[104:105]
	v_mov_b32_dpp v98, v98 row_ror:8 row_mask:0xf bank_mask:0xf
	v_mov_b32_dpp v111, v100 row_ror:8 row_mask:0xf bank_mask:0xf
	v_lshl_add_u64 v[104:105], s[10:11], 0, v[104:105]
	v_cndmask_b32_e64 v100, v108, v111, s[2:3]
	v_cndmask_b32_e64 v101, v109, v98, s[2:3]
	v_lshl_add_u64 v[104:105], v[104:105], 0, v[122:123]
	global_store_dwordx4 v[104:105], v[100:103], off nt
	v_cndmask_b32_e64 v96, v111, v106, s[2:3]
	v_cndmask_b32_e64 v97, v98, v107, s[2:3]
	v_add_co_u32_e32 v100, vcc, s79, v104
	v_cndmask_b32_e64 v98, v112, v110, s[2:3]
	v_cndmask_b32_e64 v99, v113, v99, s[2:3]
	v_addc_co_u32_e32 v101, vcc, 0, v105, vcc
	global_store_dwordx4 v[100:101], v[96:99], off nt
	v_max_f32_e32 v33, 0, v33
	v_max_f32_e32 v32, 0, v32
	v_max_f32_e32 v47, 0, v47
	v_max_f32_e32 v46, 0, v46
	v_max_f32_e32 v43, 0, v43
	v_max_f32_e32 v42, 0, v42
	v_max_f32_e32 v35, 0, v35
	v_max_f32_e32 v34, 0, v34
	v_max_f32_e32 v29, 0, v29
	v_max_f32_e32 v28, 0, v28
	v_max_f32_e32 v25, 0, v25
	v_max_f32_e32 v24, 0, v24
	v_max_f32_e32 v23, 0, v23
	v_max_f32_e32 v22, 0, v22
	v_max_f32_e32 v21, 0, v21
	v_max_f32_e32 v20, 0, v20
	v_max_f32_e32 v17, 0, v17
	v_max_f32_e32 v16, 0, v16
	v_max_f32_e32 v31, 0, v31
	v_max_f32_e32 v30, 0, v30
	v_max_f32_e32 v27, 0, v27
	v_max_f32_e32 v26, 0, v26
	v_max_f32_e32 v19, 0, v19
	v_max_f32_e32 v18, 0, v18
	v_max_f32_e32 v15, 0, v15
	v_max_f32_e32 v14, 0, v14
	v_max_f32_e32 v13, 0, v13
	v_max_f32_e32 v12, 0, v12
	v_max_f32_e32 v11, 0, v11
	v_max_f32_e32 v10, 0, v10
	v_max_f32_e32 v9, 0, v9
	v_max_f32_e32 v8, 0, v8
	v_max_f32_e32 v1, 0, v1
	v_max_f32_e32 v0, 0, v0
	v_max_f32_e32 v7, 0, v7
	v_max_f32_e32 v6, 0, v6
	v_max_f32_e32 v5, 0, v5
	v_max_f32_e32 v4, 0, v4
	v_max_f32_e32 v3, 0, v3
	v_max_f32_e32 v2, 0, v2
	s_waitcnt vmcnt(9)
; __device__ __forceinline__ u32x4 pack8(f32x4 a, f32x4 b) { u32x4 w; w.x = cvt_pk_bf16(a[0], a[1]); w.y = cvt_pk_bf16(a[2], a[3]); w.z = cvt_pk_bf16(b[0], b[1]); w.w = cvt_pk_bf16(b[2], b[3]); return w; }
; __device__ __forceinline__ float rs_of(const float* ss, int row) { return 1.0f / sqrtf(ss[row] * (1.0f / 2048.0f) + 1e-5f); }
;     __device__ __forceinline__ void operator()(const f32x4 (&acc)[2][2][4][2], const Unit& u, int wr, int wc, int fr, int fq) const {
;     ...
;             for (int m = 0; m < 4; ++m) {
;                 const int row = row0 + ai * HALF + m * 16; const float rr = ss ? rs_of(ss, row) : 1.0f;
;                 u32x4 v[2];
; #pragma unroll
;                 for (int bj = 0; bj < 2; ++bj) {
;                     f32x4 a = __builtin_elementwise_max(acc[ai][bj][m][0], z) * rr, b = __builtin_elementwise_max(acc[ai][bj][m][1], z) * rr;
;                     v[bj] = pack8(a * a, b * b);
;                 }
;                 line_xchg(v[0], v[1], hb);
;                 bf16_t* p = O + (size_t)(srow0 + ai * HALF + m * 16) * ldc + scol;
;                 __builtin_nontemporal_store(v[0], (u32x4*)p); __builtin_nontemporal_store(v[1], (u32x4*)(p + (size_t)8 * ldc));
;             }
	v_fmamk_f32 v96, v162, 0x3a000000, v205
	v_cmp_gt_f32_e32 vcc, s83, v96
	v_mul_f32_e32 v97, 0x4f800000, v96
	s_nop 0
	v_cndmask_b32_e32 v96, v96, v97, vcc
	v_sqrt_f32_e32 v97, v96
	s_nop 0
	v_add_u32_e32 v98, -1, v97
	v_fma_f32 v99, -v98, v97, v96
	v_cmp_ge_f32_e64 s[0:1], 0, v99
	v_add_u32_e32 v99, 1, v97
	s_nop 0
	v_cndmask_b32_e64 v98, v97, v98, s[0:1]
	v_fma_f32 v97, -v99, v97, v96
	v_cmp_lt_f32_e64 s[0:1], 0, v97
	s_nop 1
	v_cndmask_b32_e64 v97, v98, v99, s[0:1]
	v_mul_f32_e32 v98, 0x37800000, v97
	v_cndmask_b32_e32 v97, v97, v98, vcc
	v_cmp_class_f32_e32 vcc, v96, v206
	s_nop 1
	v_cndmask_b32_e32 v96, v97, v96, vcc
	v_div_scale_f32 v97, s[0:1], v96, v96, 1.0
	v_rcp_f32_e32 v98, v97
	s_nop 0
	v_fma_f32 v99, -v97, v98, 1.0
	v_fmac_f32_e32 v98, v99, v98
	v_div_scale_f32 v99, vcc, 1.0, v96, 1.0
	v_mul_f32_e32 v100, v99, v98
	v_fma_f32 v101, -v97, v100, v99
	v_fmac_f32_e32 v100, v101, v98
	v_fma_f32 v97, -v97, v100, v99
	v_div_fmas_f32 v97, v97, v98, v100
	v_div_fixup_f32 v96, v97, v96, 1.0
	v_pk_mul_f32 v[92:93], v[92:93], v[96:97] op_sel_hi:[1,0]
	v_pk_mul_f32 v[94:95], v[94:95], v[96:97] op_sel_hi:[1,0]
	v_pk_mul_f32 v[88:89], v[88:89], v[96:97] op_sel_hi:[1,0]
	v_pk_mul_f32 v[90:91], v[90:91], v[96:97] op_sel_hi:[1,0]
	v_pk_mul_f32 v[80:81], v[80:81], v[96:97] op_sel_hi:[1,0]
	v_pk_mul_f32 v[94:95], v[94:95], v[94:95]
	v_pk_mul_f32 v[92:93], v[92:93], v[92:93]
	v_pk_mul_f32 v[90:91], v[90:91], v[90:91]
	v_pk_mul_f32 v[88:89], v[88:89], v[88:89]
	v_pk_mul_f32 v[84:85], v[84:85], v[96:97] op_sel_hi:[1,0]
	v_pk_mul_f32 v[86:87], v[86:87], v[96:97] op_sel_hi:[1,0]
	v_pk_mul_f32 v[82:83], v[82:83], v[96:97] op_sel_hi:[1,0]
	v_pk_mul_f32 v[80:81], v[80:81], v[80:81]
	v_cvt_pk_bf16_f32 v92, v92, v93
	v_cvt_pk_bf16_f32 v93, v94, v95
	v_cvt_pk_bf16_f32 v88, v88, v89
	v_cvt_pk_bf16_f32 v89, v90, v91
	v_pk_mul_f32 v[86:87], v[86:87], v[86:87]
	v_pk_mul_f32 v[84:85], v[84:85], v[84:85]
	v_pk_mul_f32 v[82:83], v[82:83], v[82:83]
	v_cvt_pk_bf16_f32 v90, v84, v85
	v_cvt_pk_bf16_f32 v91, v86, v87
	v_cvt_pk_bf16_f32 v94, v80, v81
	s_nop 0
	v_cndmask_b32_e64 v81, v94, v88, s[2:3]
	v_cvt_pk_bf16_f32 v83, v82, v83
	v_cndmask_b32_e64 v82, v91, v93, s[2:3]
	v_cndmask_b32_e64 v80, v83, v89, s[2:3]
	v_mov_b32_dpp v96, v81 row_ror:8 row_mask:0xf bank_mask:0xf
	v_cndmask_b32_e64 v86, v88, v96, s[2:3]
	v_mov_b32_dpp v97, v80 row_ror:8 row_mask:0xf bank_mask:0xf
	v_or_b32_e32 v88, 32, v136
	v_cndmask_b32_e64 v87, v89, v97, s[2:3]
	v_ashrrev_i32_e32 v89, 31, v88
	v_cndmask_b32_e64 v84, v90, v92, s[2:3]
	v_lshlrev_b64 v[88:89], 14, v[88:89]
	v_mov_b32_dpp v82, v82 row_ror:8 row_mask:0xf bank_mask:0xf
	v_mov_b32_dpp v95, v84 row_ror:8 row_mask:0xf bank_mask:0xf
	v_lshl_add_u64 v[88:89], s[10:11], 0, v[88:89]
	v_cndmask_b32_e64 v84, v92, v95, s[2:3]
	v_cndmask_b32_e64 v85, v93, v82, s[2:3]
	v_lshl_add_u64 v[88:89], v[88:89], 0, v[122:123]
	global_store_dwordx4 v[88:89], v[84:87], off nt
	v_cndmask_b32_e64 v80, v95, v90, s[2:3]
	v_cndmask_b32_e64 v81, v82, v91, s[2:3]
	v_add_co_u32_e32 v84, vcc, s79, v88
	v_cndmask_b32_e64 v82, v96, v94, s[2:3]
	v_cndmask_b32_e64 v83, v97, v83, s[2:3]
	v_addc_co_u32_e32 v85, vcc, 0, v89, vcc
	global_store_dwordx4 v[84:85], v[80:83], off nt
	s_nop 1
	s_waitcnt vmcnt(10)
	v_fmamk_f32 v80, v163, 0x3a000000, v205
	v_cmp_gt_f32_e32 vcc, s83, v80
	v_mul_f32_e32 v81, 0x4f800000, v80
	s_nop 0
	v_cndmask_b32_e32 v80, v80, v81, vcc
	v_sqrt_f32_e32 v81, v80
	s_nop 0
	v_add_u32_e32 v82, -1, v81
	v_fma_f32 v83, -v82, v81, v80
	v_cmp_ge_f32_e64 s[0:1], 0, v83
	v_add_u32_e32 v83, 1, v81
	s_nop 0
	v_cndmask_b32_e64 v82, v81, v82, s[0:1]
	v_fma_f32 v81, -v83, v81, v80
	v_cmp_lt_f32_e64 s[0:1], 0, v81
	s_nop 1
	v_cndmask_b32_e64 v81, v82, v83, s[0:1]
	v_mul_f32_e32 v82, 0x37800000, v81
	v_cndmask_b32_e32 v81, v81, v82, vcc
	v_cmp_class_f32_e32 vcc, v80, v206
	s_nop 1
	v_cndmask_b32_e32 v80, v81, v80, vcc
	v_div_scale_f32 v81, s[0:1], v80, v80, 1.0
	v_rcp_f32_e32 v82, v81
	s_nop 0
	v_fma_f32 v83, -v81, v82, 1.0
	v_fmac_f32_e32 v82, v83, v82
	v_div_scale_f32 v83, vcc, 1.0, v80, 1.0
	v_mul_f32_e32 v84, v83, v82
	v_fma_f32 v85, -v81, v84, v83
	v_fmac_f32_e32 v84, v85, v82
	v_fma_f32 v81, -v81, v84, v83
	v_div_fmas_f32 v81, v81, v82, v84
	v_div_fixup_f32 v80, v81, v80, 1.0
	v_pk_mul_f32 v[76:77], v[76:77], v[80:81] op_sel_hi:[1,0]
	v_pk_mul_f32 v[78:79], v[78:79], v[80:81] op_sel_hi:[1,0]
	v_pk_mul_f32 v[72:73], v[72:73], v[80:81] op_sel_hi:[1,0]
	v_pk_mul_f32 v[74:75], v[74:75], v[80:81] op_sel_hi:[1,0]
	v_pk_mul_f32 v[64:65], v[64:65], v[80:81] op_sel_hi:[1,0]
	v_pk_mul_f32 v[78:79], v[78:79], v[78:79]
	v_pk_mul_f32 v[76:77], v[76:77], v[76:77]
	v_pk_mul_f32 v[74:75], v[74:75], v[74:75]
	v_pk_mul_f32 v[72:73], v[72:73], v[72:73]
	v_pk_mul_f32 v[68:69], v[68:69], v[80:81] op_sel_hi:[1,0]
	v_pk_mul_f32 v[70:71], v[70:71], v[80:81] op_sel_hi:[1,0]
	v_pk_mul_f32 v[66:67], v[66:67], v[80:81] op_sel_hi:[1,0]
	v_pk_mul_f32 v[64:65], v[64:65], v[64:65]
	v_cvt_pk_bf16_f32 v76, v76, v77
	v_cvt_pk_bf16_f32 v77, v78, v79
	v_cvt_pk_bf16_f32 v72, v72, v73
	v_cvt_pk_bf16_f32 v73, v74, v75
	v_pk_mul_f32 v[70:71], v[70:71], v[70:71]
	v_pk_mul_f32 v[68:69], v[68:69], v[68:69]
	v_pk_mul_f32 v[66:67], v[66:67], v[66:67]
	v_cvt_pk_bf16_f32 v74, v68, v69
	v_cvt_pk_bf16_f32 v75, v70, v71
	v_cvt_pk_bf16_f32 v78, v64, v65
	s_nop 0
	v_cndmask_b32_e64 v65, v78, v72, s[2:3]
	v_cvt_pk_bf16_f32 v67, v66, v67
	v_cndmask_b32_e64 v66, v75, v77, s[2:3]
	v_cndmask_b32_e64 v64, v67, v73, s[2:3]
	v_mov_b32_dpp v80, v65 row_ror:8 row_mask:0xf bank_mask:0xf
	v_cndmask_b32_e64 v70, v72, v80, s[2:3]
	v_mov_b32_dpp v81, v64 row_ror:8 row_mask:0xf bank_mask:0xf
	v_or_b32_e32 v72, 48, v136
	v_cndmask_b32_e64 v71, v73, v81, s[2:3]
	v_ashrrev_i32_e32 v73, 31, v72
	v_cndmask_b32_e64 v68, v74, v76, s[2:3]
	v_lshlrev_b64 v[72:73], 14, v[72:73]
	v_mov_b32_dpp v66, v66 row_ror:8 row_mask:0xf bank_mask:0xf
	v_mov_b32_dpp v79, v68 row_ror:8 row_mask:0xf bank_mask:0xf
	v_lshl_add_u64 v[72:73], s[10:11], 0, v[72:73]
	v_cndmask_b32_e64 v68, v76, v79, s[2:3]
	v_cndmask_b32_e64 v69, v77, v66, s[2:3]
	v_lshl_add_u64 v[72:73], v[72:73], 0, v[122:123]
	global_store_dwordx4 v[72:73], v[68:71], off nt
	v_cndmask_b32_e64 v64, v79, v74, s[2:3]
	v_cndmask_b32_e64 v65, v66, v75, s[2:3]
	v_add_co_u32_e32 v68, vcc, s79, v72
	v_cndmask_b32_e64 v66, v80, v78, s[2:3]
	v_cndmask_b32_e64 v67, v81, v67, s[2:3]
	v_addc_co_u32_e32 v69, vcc, 0, v73, vcc
	global_store_dwordx4 v[68:69], v[64:67], off nt
	s_nop 1
	s_waitcnt vmcnt(11)
; __device__ __forceinline__ u32x4 pack8(f32x4 a, f32x4 b) { u32x4 w; w.x = cvt_pk_bf16(a[0], a[1]); w.y = cvt_pk_bf16(a[2], a[3]); w.z = cvt_pk_bf16(b[0], b[1]); w.w = cvt_pk_bf16(b[2], b[3]); return w; }
; __device__ __forceinline__ float rs_of(const float* ss, int row) { return 1.0f / sqrtf(ss[row] * (1.0f / 2048.0f) + 1e-5f); }
;     __device__ __forceinline__ void operator()(const f32x4 (&acc)[2][2][4][2], const Unit& u, int wr, int wc, int fr, int fq) const {
;     ...
;             for (int m = 0; m < 4; ++m) {
;                 const int row = row0 + ai * HALF + m * 16; const float rr = ss ? rs_of(ss, row) : 1.0f;
;                 u32x4 v[2];
; #pragma unroll
;                 for (int bj = 0; bj < 2; ++bj) {
;                     f32x4 a = __builtin_elementwise_max(acc[ai][bj][m][0], z) * rr, b = __builtin_elementwise_max(acc[ai][bj][m][1], z) * rr;
;                     v[bj] = pack8(a * a, b * b);
;                 }
;                 line_xchg(v[0], v[1], hb);
;                 bf16_t* p = O + (size_t)(srow0 + ai * HALF + m * 16) * ldc + scol;
;                 __builtin_nontemporal_store(v[0], (u32x4*)p); __builtin_nontemporal_store(v[1], (u32x4*)(p + (size_t)8 * ldc));
;             }
	v_fmamk_f32 v64, v164, 0x3a000000, v205
	v_cmp_gt_f32_e32 vcc, s83, v64
	v_mul_f32_e32 v65, 0x4f800000, v64
	s_nop 0
	v_cndmask_b32_e32 v64, v64, v65, vcc
	v_sqrt_f32_e32 v65, v64
	s_nop 0
	v_add_u32_e32 v66, -1, v65
	v_fma_f32 v67, -v66, v65, v64
	v_cmp_ge_f32_e64 s[0:1], 0, v67
	v_add_u32_e32 v67, 1, v65
	s_nop 0
	v_cndmask_b32_e64 v66, v65, v66, s[0:1]
	v_fma_f32 v65, -v67, v65, v64
	v_cmp_lt_f32_e64 s[0:1], 0, v65
	s_nop 1
	v_cndmask_b32_e64 v65, v66, v67, s[0:1]
	v_mul_f32_e32 v66, 0x37800000, v65
	v_cndmask_b32_e32 v65, v65, v66, vcc
	v_cmp_class_f32_e32 vcc, v64, v206
	s_nop 1
	v_cndmask_b32_e32 v64, v65, v64, vcc
	v_div_scale_f32 v65, s[0:1], v64, v64, 1.0
	v_rcp_f32_e32 v66, v65
	s_mov_b32 s0, 0x200000
	v_fma_f32 v67, -v65, v66, 1.0
	v_fmac_f32_e32 v66, v67, v66
	v_div_scale_f32 v67, vcc, 1.0, v64, 1.0
	v_mul_f32_e32 v68, v67, v66
	v_fma_f32 v69, -v65, v68, v67
	v_fmac_f32_e32 v68, v69, v66
	v_fma_f32 v65, -v65, v68, v67
	v_div_fmas_f32 v65, v65, v66, v68
	v_div_fixup_f32 v64, v65, v64, 1.0
	v_pk_mul_f32 v[60:61], v[60:61], v[64:65] op_sel_hi:[1,0]
	v_pk_mul_f32 v[62:63], v[62:63], v[64:65] op_sel_hi:[1,0]
	v_pk_mul_f32 v[56:57], v[56:57], v[64:65] op_sel_hi:[1,0]
	v_pk_mul_f32 v[58:59], v[58:59], v[64:65] op_sel_hi:[1,0]
	v_pk_mul_f32 v[48:49], v[48:49], v[64:65] op_sel_hi:[1,0]
	v_pk_mul_f32 v[62:63], v[62:63], v[62:63]
	v_pk_mul_f32 v[60:61], v[60:61], v[60:61]
	v_pk_mul_f32 v[58:59], v[58:59], v[58:59]
	v_pk_mul_f32 v[56:57], v[56:57], v[56:57]
	v_pk_mul_f32 v[52:53], v[52:53], v[64:65] op_sel_hi:[1,0]
	v_pk_mul_f32 v[54:55], v[54:55], v[64:65] op_sel_hi:[1,0]
	v_pk_mul_f32 v[50:51], v[50:51], v[64:65] op_sel_hi:[1,0]
	v_pk_mul_f32 v[48:49], v[48:49], v[48:49]
	v_cvt_pk_bf16_f32 v60, v60, v61
	v_cvt_pk_bf16_f32 v61, v62, v63
	v_cvt_pk_bf16_f32 v56, v56, v57
	v_cvt_pk_bf16_f32 v57, v58, v59
	v_pk_mul_f32 v[54:55], v[54:55], v[54:55]
	v_pk_mul_f32 v[52:53], v[52:53], v[52:53]
	v_pk_mul_f32 v[50:51], v[50:51], v[50:51]
	v_cvt_pk_bf16_f32 v58, v52, v53
	v_cvt_pk_bf16_f32 v59, v54, v55
	v_cvt_pk_bf16_f32 v62, v48, v49
	s_nop 0
	v_cndmask_b32_e64 v49, v62, v56, s[2:3]
	v_cvt_pk_bf16_f32 v51, v50, v51
	v_cndmask_b32_e64 v50, v59, v61, s[2:3]
	v_cndmask_b32_e64 v48, v51, v57, s[2:3]
	v_cndmask_b32_e64 v52, v58, v60, s[2:3]
	v_mov_b32_dpp v64, v49 row_ror:8 row_mask:0xf bank_mask:0xf
	v_mov_b32_dpp v50, v50 row_ror:8 row_mask:0xf bank_mask:0xf
	v_mov_b32_dpp v63, v52 row_ror:8 row_mask:0xf bank_mask:0xf
	v_mov_b32_dpp v65, v48 row_ror:8 row_mask:0xf bank_mask:0xf
	v_cndmask_b32_e64 v54, v56, v64, s[2:3]
	v_add_co_u32_e32 v56, vcc, s0, v120
	v_cndmask_b32_e64 v52, v60, v63, s[2:3]
	v_cndmask_b32_e64 v53, v61, v50, s[2:3]
	v_cndmask_b32_e64 v55, v57, v65, s[2:3]
	v_addc_co_u32_e32 v57, vcc, 0, v121, vcc
	s_mov_b32 s0, 0x220000
	global_store_dwordx4 v[56:57], v[52:55], off nt
	v_cndmask_b32_e64 v48, v63, v58, s[2:3]
	v_cndmask_b32_e64 v49, v50, v59, s[2:3]
	v_add_co_u32_e32 v52, vcc, s0, v120
	v_cndmask_b32_e64 v50, v64, v62, s[2:3]
	v_cndmask_b32_e64 v51, v65, v51, s[2:3]
	v_addc_co_u32_e32 v53, vcc, 0, v121, vcc
	global_store_dwordx4 v[52:53], v[48:51], off nt
	s_nop 1
	s_waitcnt vmcnt(12)
	v_fmamk_f32 v48, v165, 0x3a000000, v205
	v_cmp_gt_f32_e32 vcc, s83, v48
	v_mul_f32_e32 v49, 0x4f800000, v48
	s_nop 0
	v_cndmask_b32_e32 v48, v48, v49, vcc
	v_sqrt_f32_e32 v49, v48
	s_nop 0
	v_add_u32_e32 v50, -1, v49
	v_fma_f32 v51, -v50, v49, v48
	v_cmp_ge_f32_e64 s[0:1], 0, v51
	v_add_u32_e32 v51, 1, v49
	s_nop 0
	v_cndmask_b32_e64 v50, v49, v50, s[0:1]
	v_fma_f32 v49, -v51, v49, v48
	v_cmp_lt_f32_e64 s[0:1], 0, v49
	s_nop 1
	v_cndmask_b32_e64 v49, v50, v51, s[0:1]
	v_mul_f32_e32 v50, 0x37800000, v49
	v_cndmask_b32_e32 v49, v49, v50, vcc
	v_cmp_class_f32_e32 vcc, v48, v206
	s_nop 1
	v_cndmask_b32_e32 v48, v49, v48, vcc
	v_div_scale_f32 v49, s[0:1], v48, v48, 1.0
	v_rcp_f32_e32 v50, v49
	s_mov_b32 s0, 0x240000
	v_fma_f32 v51, -v49, v50, 1.0
	v_fmac_f32_e32 v50, v51, v50
	v_div_scale_f32 v51, vcc, 1.0, v48, 1.0
	v_mul_f32_e32 v52, v51, v50
	v_fma_f32 v53, -v49, v52, v51
	v_fmac_f32_e32 v52, v53, v50
	v_fma_f32 v49, -v49, v52, v51
	v_div_fmas_f32 v49, v49, v50, v52
	v_div_fixup_f32 v48, v49, v48, 1.0
	v_pk_mul_f32 v[44:45], v[44:45], v[48:49] op_sel_hi:[1,0]
	v_pk_mul_f32 v[40:41], v[40:41], v[48:49] op_sel_hi:[1,0]
	v_pk_mul_f32 v[36:37], v[36:37], v[48:49] op_sel_hi:[1,0]
	v_pk_mul_f32 v[38:39], v[38:39], v[48:49] op_sel_hi:[1,0]
	v_pk_mul_f32 v[32:33], v[32:33], v[48:49] op_sel_hi:[1,0]
	v_pk_mul_f32 v[46:47], v[46:47], v[48:49] op_sel_hi:[1,0]
	v_pk_mul_f32 v[42:43], v[42:43], v[48:49] op_sel_hi:[1,0]
	v_pk_mul_f32 v[44:45], v[44:45], v[44:45]
	v_pk_mul_f32 v[40:41], v[40:41], v[40:41]
	v_pk_mul_f32 v[34:35], v[34:35], v[48:49] op_sel_hi:[1,0]
	v_pk_mul_f32 v[38:39], v[38:39], v[38:39]
	v_pk_mul_f32 v[36:37], v[36:37], v[36:37]
	v_pk_mul_f32 v[32:33], v[32:33], v[32:33]
	v_pk_mul_f32 v[46:47], v[46:47], v[46:47]
	v_pk_mul_f32 v[42:43], v[42:43], v[42:43]
	v_cvt_pk_bf16_f32 v44, v44, v45
	v_cvt_pk_bf16_f32 v45, v46, v47
	v_cvt_pk_bf16_f32 v40, v40, v41
	v_pk_mul_f32 v[34:35], v[34:35], v[34:35]
	v_cvt_pk_bf16_f32 v41, v42, v43
	v_cvt_pk_bf16_f32 v36, v36, v37
	v_cvt_pk_bf16_f32 v37, v38, v39
	v_cvt_pk_bf16_f32 v38, v32, v33
	s_nop 0
	v_cndmask_b32_e64 v33, v38, v40, s[2:3]
	v_cvt_pk_bf16_f32 v39, v34, v35
	v_cndmask_b32_e64 v34, v37, v45, s[2:3]
	v_cndmask_b32_e64 v32, v39, v41, s[2:3]
	v_cndmask_b32_e64 v35, v36, v44, s[2:3]
	v_mov_b32_dpp v46, v33 row_ror:8 row_mask:0xf bank_mask:0xf
	v_mov_b32_dpp v43, v34 row_ror:8 row_mask:0xf bank_mask:0xf
	v_mov_b32_dpp v42, v35 row_ror:8 row_mask:0xf bank_mask:0xf
	v_mov_b32_dpp v47, v32 row_ror:8 row_mask:0xf bank_mask:0xf
	v_cndmask_b32_e64 v34, v40, v46, s[2:3]
	v_add_co_u32_e32 v40, vcc, s0, v120
	v_cndmask_b32_e64 v32, v44, v42, s[2:3]
	v_cndmask_b32_e64 v33, v45, v43, s[2:3]
	v_cndmask_b32_e64 v35, v41, v47, s[2:3]
	v_addc_co_u32_e32 v41, vcc, 0, v121, vcc
	s_mov_b32 s0, 0x260000
	global_store_dwordx4 v[40:41], v[32:35], off nt
	v_cndmask_b32_e64 v36, v42, v36, s[2:3]
	v_cndmask_b32_e64 v37, v43, v37, s[2:3]
	v_add_co_u32_e32 v32, vcc, s0, v120
	v_cndmask_b32_e64 v38, v46, v38, s[2:3]
	v_cndmask_b32_e64 v39, v47, v39, s[2:3]
	v_addc_co_u32_e32 v33, vcc, 0, v121, vcc
	global_store_dwordx4 v[32:33], v[36:39], off nt
	s_nop 1
	s_waitcnt vmcnt(13)
; __device__ __forceinline__ u32x4 pack8(f32x4 a, f32x4 b) { u32x4 w; w.x = cvt_pk_bf16(a[0], a[1]); w.y = cvt_pk_bf16(a[2], a[3]); w.z = cvt_pk_bf16(b[0], b[1]); w.w = cvt_pk_bf16(b[2], b[3]); return w; }
; __device__ __forceinline__ float rs_of(const float* ss, int row) { return 1.0f / sqrtf(ss[row] * (1.0f / 2048.0f) + 1e-5f); }
;     __device__ __forceinline__ void operator()(const f32x4 (&acc)[2][2][4][2], const Unit& u, int wr, int wc, int fr, int fq) const {
;     ...
;             for (int m = 0; m < 4; ++m) {
;                 const int row = row0 + ai * HALF + m * 16; const float rr = ss ? rs_of(ss, row) : 1.0f;
;                 u32x4 v[2];
; #pragma unroll
;                 for (int bj = 0; bj < 2; ++bj) {
;                     f32x4 a = __builtin_elementwise_max(acc[ai][bj][m][0], z) * rr, b = __builtin_elementwise_max(acc[ai][bj][m][1], z) * rr;
;                     v[bj] = pack8(a * a, b * b);
;                 }
;                 line_xchg(v[0], v[1], hb);
;                 bf16_t* p = O + (size_t)(srow0 + ai * HALF + m * 16) * ldc + scol;
;                 __builtin_nontemporal_store(v[0], (u32x4*)p); __builtin_nontemporal_store(v[1], (u32x4*)(p + (size_t)8 * ldc));
;             }
	v_fmamk_f32 v32, v166, 0x3a000000, v205
	v_cmp_gt_f32_e32 vcc, s83, v32
	v_mul_f32_e32 v33, 0x4f800000, v32
	s_nop 0
	v_cndmask_b32_e32 v32, v32, v33, vcc
	v_sqrt_f32_e32 v33, v32
	s_nop 0
	v_add_u32_e32 v34, -1, v33
	v_fma_f32 v35, -v34, v33, v32
	v_cmp_ge_f32_e64 s[0:1], 0, v35
	v_add_u32_e32 v35, 1, v33
	s_nop 0
	v_cndmask_b32_e64 v34, v33, v34, s[0:1]
	v_fma_f32 v33, -v35, v33, v32
	v_cmp_lt_f32_e64 s[0:1], 0, v33
	s_nop 1
	v_cndmask_b32_e64 v33, v34, v35, s[0:1]
	v_mul_f32_e32 v34, 0x37800000, v33
	v_cndmask_b32_e32 v33, v33, v34, vcc
	v_cmp_class_f32_e32 vcc, v32, v206
	s_nop 1
	v_cndmask_b32_e32 v32, v33, v32, vcc
	v_div_scale_f32 v33, s[0:1], v32, v32, 1.0
	v_rcp_f32_e32 v34, v33
	s_mov_b32 s0, 0x280000
	v_fma_f32 v35, -v33, v34, 1.0
	v_fmac_f32_e32 v34, v35, v34
	v_div_scale_f32 v35, vcc, 1.0, v32, 1.0
	v_mul_f32_e32 v36, v35, v34
	v_fma_f32 v37, -v33, v36, v35
	v_fmac_f32_e32 v36, v37, v34
	v_fma_f32 v33, -v33, v36, v35
	v_div_fmas_f32 v33, v33, v34, v36
	v_div_fixup_f32 v32, v33, v32, 1.0
	v_pk_mul_f32 v[28:29], v[28:29], v[32:33] op_sel_hi:[1,0]
	v_pk_mul_f32 v[24:25], v[24:25], v[32:33] op_sel_hi:[1,0]
	v_pk_mul_f32 v[20:21], v[20:21], v[32:33] op_sel_hi:[1,0]
	v_pk_mul_f32 v[22:23], v[22:23], v[32:33] op_sel_hi:[1,0]
	v_pk_mul_f32 v[16:17], v[16:17], v[32:33] op_sel_hi:[1,0]
	v_pk_mul_f32 v[30:31], v[30:31], v[32:33] op_sel_hi:[1,0]
	v_pk_mul_f32 v[26:27], v[26:27], v[32:33] op_sel_hi:[1,0]
	v_pk_mul_f32 v[28:29], v[28:29], v[28:29]
	v_pk_mul_f32 v[24:25], v[24:25], v[24:25]
	v_pk_mul_f32 v[18:19], v[18:19], v[32:33] op_sel_hi:[1,0]
	v_pk_mul_f32 v[22:23], v[22:23], v[22:23]
	v_pk_mul_f32 v[20:21], v[20:21], v[20:21]
	v_pk_mul_f32 v[16:17], v[16:17], v[16:17]
	v_pk_mul_f32 v[30:31], v[30:31], v[30:31]
	v_pk_mul_f32 v[26:27], v[26:27], v[26:27]
	v_cvt_pk_bf16_f32 v28, v28, v29
	v_cvt_pk_bf16_f32 v29, v30, v31
	v_cvt_pk_bf16_f32 v24, v24, v25
	v_pk_mul_f32 v[18:19], v[18:19], v[18:19]
	v_cvt_pk_bf16_f32 v25, v26, v27
	v_cvt_pk_bf16_f32 v20, v20, v21
	v_cvt_pk_bf16_f32 v21, v22, v23
	v_cvt_pk_bf16_f32 v22, v16, v17
	s_nop 0
	v_cndmask_b32_e64 v17, v22, v24, s[2:3]
	v_cvt_pk_bf16_f32 v23, v18, v19
	v_cndmask_b32_e64 v18, v21, v29, s[2:3]
	v_cndmask_b32_e64 v16, v23, v25, s[2:3]
	v_cndmask_b32_e64 v19, v20, v28, s[2:3]
	v_mov_b32_dpp v30, v17 row_ror:8 row_mask:0xf bank_mask:0xf
	v_mov_b32_dpp v27, v18 row_ror:8 row_mask:0xf bank_mask:0xf
	v_mov_b32_dpp v26, v19 row_ror:8 row_mask:0xf bank_mask:0xf
	v_mov_b32_dpp v31, v16 row_ror:8 row_mask:0xf bank_mask:0xf
	v_cndmask_b32_e64 v18, v24, v30, s[2:3]
	v_add_co_u32_e32 v24, vcc, s0, v120
	v_cndmask_b32_e64 v16, v28, v26, s[2:3]
	v_cndmask_b32_e64 v17, v29, v27, s[2:3]
	v_cndmask_b32_e64 v19, v25, v31, s[2:3]
	v_addc_co_u32_e32 v25, vcc, 0, v121, vcc
	s_mov_b32 s0, 0x2a0000
	global_store_dwordx4 v[24:25], v[16:19], off nt
	v_cndmask_b32_e64 v20, v26, v20, s[2:3]
	v_cndmask_b32_e64 v21, v27, v21, s[2:3]
	v_add_co_u32_e32 v16, vcc, s0, v120
	v_cndmask_b32_e64 v22, v30, v22, s[2:3]
	v_cndmask_b32_e64 v23, v31, v23, s[2:3]
	v_addc_co_u32_e32 v17, vcc, 0, v121, vcc
	global_store_dwordx4 v[16:17], v[20:23], off nt
	s_nop 1
	s_waitcnt vmcnt(14)
	v_fmamk_f32 v16, v167, 0x3a000000, v205
	v_cmp_gt_f32_e32 vcc, s83, v16
	v_mul_f32_e32 v17, 0x4f800000, v16
	s_nop 0
	v_cndmask_b32_e32 v16, v16, v17, vcc
	v_sqrt_f32_e32 v17, v16
	s_nop 0
	v_add_u32_e32 v18, -1, v17
	v_fma_f32 v19, -v18, v17, v16
	v_cmp_ge_f32_e64 s[0:1], 0, v19
	v_add_u32_e32 v19, 1, v17
	s_nop 0
	v_cndmask_b32_e64 v18, v17, v18, s[0:1]
	v_fma_f32 v17, -v19, v17, v16
	v_cmp_lt_f32_e64 s[0:1], 0, v17
	s_nop 1
	v_cndmask_b32_e64 v17, v18, v19, s[0:1]
	v_mul_f32_e32 v18, 0x37800000, v17
	v_cndmask_b32_e32 v17, v17, v18, vcc
	v_cmp_class_f32_e32 vcc, v16, v206
	s_nop 1
	v_cndmask_b32_e32 v16, v17, v16, vcc
	v_div_scale_f32 v17, s[0:1], v16, v16, 1.0
	v_rcp_f32_e32 v18, v17
	s_mov_b64 s[0:1], -1
	v_fma_f32 v19, -v17, v18, 1.0
	v_fmac_f32_e32 v18, v19, v18
	v_div_scale_f32 v19, vcc, 1.0, v16, 1.0
	v_mul_f32_e32 v20, v19, v18
	v_fma_f32 v21, -v17, v20, v19
	v_fmac_f32_e32 v20, v21, v18
	v_fma_f32 v17, -v17, v20, v19
	v_div_fmas_f32 v17, v17, v18, v20
	v_div_fixup_f32 v16, v17, v16, 1.0
	v_pk_mul_f32 v[12:13], v[12:13], v[16:17] op_sel_hi:[1,0]
	v_pk_mul_f32 v[14:15], v[14:15], v[16:17] op_sel_hi:[1,0]
	v_pk_mul_f32 v[8:9], v[8:9], v[16:17] op_sel_hi:[1,0]
	v_pk_mul_f32 v[10:11], v[10:11], v[16:17] op_sel_hi:[1,0]
	v_pk_mul_f32 v[0:1], v[0:1], v[16:17] op_sel_hi:[1,0]
	v_pk_mul_f32 v[14:15], v[14:15], v[14:15]
	v_pk_mul_f32 v[12:13], v[12:13], v[12:13]
	v_pk_mul_f32 v[10:11], v[10:11], v[10:11]
	v_pk_mul_f32 v[8:9], v[8:9], v[8:9]
	v_pk_mul_f32 v[4:5], v[4:5], v[16:17] op_sel_hi:[1,0]
	v_pk_mul_f32 v[6:7], v[6:7], v[16:17] op_sel_hi:[1,0]
	v_pk_mul_f32 v[2:3], v[2:3], v[16:17] op_sel_hi:[1,0]
	v_pk_mul_f32 v[0:1], v[0:1], v[0:1]
	v_cvt_pk_bf16_f32 v12, v12, v13
	v_cvt_pk_bf16_f32 v13, v14, v15
	v_cvt_pk_bf16_f32 v8, v8, v9
	v_cvt_pk_bf16_f32 v9, v10, v11
	v_pk_mul_f32 v[6:7], v[6:7], v[6:7]
	v_pk_mul_f32 v[4:5], v[4:5], v[4:5]
	v_pk_mul_f32 v[2:3], v[2:3], v[2:3]
	v_cvt_pk_bf16_f32 v10, v4, v5
	v_cvt_pk_bf16_f32 v11, v6, v7
	v_cvt_pk_bf16_f32 v14, v0, v1
	s_nop 0
	v_cndmask_b32_e64 v1, v14, v8, s[2:3]
	v_cvt_pk_bf16_f32 v3, v2, v3
	v_cndmask_b32_e64 v2, v11, v13, s[2:3]
	v_cndmask_b32_e64 v0, v3, v9, s[2:3]
	v_cndmask_b32_e64 v4, v10, v12, s[2:3]
	v_mov_b32_dpp v16, v1 row_ror:8 row_mask:0xf bank_mask:0xf
	v_mov_b32_dpp v2, v2 row_ror:8 row_mask:0xf bank_mask:0xf
	v_mov_b32_dpp v15, v4 row_ror:8 row_mask:0xf bank_mask:0xf
	v_mov_b32_dpp v17, v0 row_ror:8 row_mask:0xf bank_mask:0xf
	v_cndmask_b32_e64 v6, v8, v16, s[2:3]
	v_add_co_u32_e32 v8, vcc, 0x2c0000, v120
	v_cndmask_b32_e64 v4, v12, v15, s[2:3]
	v_cndmask_b32_e64 v5, v13, v2, s[2:3]
	v_cndmask_b32_e64 v7, v9, v17, s[2:3]
	v_addc_co_u32_e32 v9, vcc, 0, v121, vcc
	global_store_dwordx4 v[8:9], v[4:7], off nt
	v_cndmask_b32_e64 v0, v15, v10, s[2:3]
	v_cndmask_b32_e64 v1, v2, v11, s[2:3]
	v_add_co_u32_e32 v4, vcc, 0x2e0000, v120
	v_cndmask_b32_e64 v2, v16, v14, s[2:3]
	s_nop 0
	v_addc_co_u32_e32 v5, vcc, 0, v121, vcc
	v_cndmask_b32_e64 v3, v17, v3, s[2:3]
	s_andn2_b64 vcc, exec, s[4:5]
	global_store_dwordx4 v[4:5], v[0:3], off nt
	s_cbranch_vccnz .LBB0_702
	s_andn2_b64 vcc, exec, s[8:9]
	s_cbranch_vccnz .LBB0_701
	s_barrier
	s_branch .LBB0_701
